# phase_mla_post token loop hand-written (all inputs up front, 13 interleaved DPP reductions)
# speedup vs baseline: 1.1094x; 1.0055x over previous
; __device__ __forceinline__ void phase_mla_post(const Params p, int l, char* smem) {
;     ...
;   const float* ng = (const float*)p.in[I_NOPEG] + l * 256;
;   const float* rg = (const float*)p.in[I_ROPEG] + l * 128;
;   const int* pos = (const int*)p.in[I_POS];
;   const float qscale = 0.07216878364870322f * LOG2E;
;   const int fi = lane & 31;
;   const float inv_freq = powf(10000.f, -(float)fi / 32.f);
.LBB0_249:
	s_andn2_b64 vcc, exec, s[0:1]
	s_cbranch_vccnz .LBB0_532
	v_readlane_b32 s0, v244, 45
	s_cmp_lt_i32 s0, 2
	s_mov_b64 s[0:1], -1
	s_cbranch_scc1 .LBB0_313
	v_readlane_b32 s0, v244, 45
	s_cmp_gt_i32 s0, 2
	s_mov_b64 s[0:1], -1
	s_cbranch_scc0 .LBB0_292
	s_waitcnt vmcnt(14)
	v_mov_b32_e32 v1, v171
	v_mov_b32_e32 v0, v171
	s_mov_b32 s0, s73
	v_ashrrev_i32_e32 v0, 6, v0
	s_nop 0
	v_lshl_add_u32 v0, s0, 2, v0
	s_movk_i32 s0, 0x2000
	v_cmp_gt_i32_e32 vcc, s0, v0
	s_and_saveexec_b64 s[2:3], vcc
	s_cbranch_execz .LBB0_291
	v_and_b32_e32 v2, 31, v1
	v_cvt_f32_ubyte0_e32 v3, v2
	s_waitcnt vmcnt(2)
	v_mul_f32_e32 v18, 0xbd000000, v3
	v_cmp_eq_f32_e32 vcc, 0, v18
	s_mov_b32 s0, 0x3f2aaaab
	v_readlane_b32 s36, v247, 12
	v_cndmask_b32_e64 v3, v211, 1.0, vcc
	v_frexp_mant_f32_e32 v4, v3
	v_cmp_gt_f32_e64 s[0:1], s0, v4
	v_readlane_b32 s46, v247, 22
	v_readlane_b32 s47, v247, 23
	v_cndmask_b32_e64 v5, 1.0, 2.0, s[0:1]
	v_mul_f32_e32 v4, v4, v5
	s_waitcnt lgkmcnt(0)
	v_add_f32_e32 v7, 1.0, v4
	v_rcp_f32_e32 v12, v7
	v_add_f32_e32 v5, -1.0, v7
	v_sub_f32_e32 v9, v4, v5
	v_add_f32_e32 v5, -1.0, v4
	v_mul_f32_e32 v13, v5, v12
	v_mul_f32_e32 v6, v7, v13
	v_fma_f32 v8, v13, v7, -v6
	v_fmac_f32_e32 v8, v13, v9
	v_add_f32_e32 v4, v6, v8
	v_sub_f32_e32 v7, v5, v4
	v_pk_add_f32 v[10:11], v[4:5], v[6:7] neg_lo:[0,1] neg_hi:[0,1]
	v_mov_b32_e32 v9, v4
	v_pk_add_f32 v[4:5], v[10:11], v[8:9] neg_lo:[0,1] neg_hi:[0,1]
	v_lshlrev_b32_e32 v168, 2, v2
	v_add_f32_e32 v4, v4, v5
	v_add_f32_e32 v4, v7, v4
	v_mul_f32_e32 v5, v12, v4
	v_add_f32_e32 v4, v13, v5
	v_sub_f32_e32 v6, v4, v13
	v_sub_f32_e32 v14, v5, v6
	v_mul_f32_e32 v5, v4, v4
	v_fma_f32 v7, v4, v4, -v5
	v_add_f32_e32 v6, v14, v14
	v_fmac_f32_e32 v7, v4, v6
	v_add_f32_e32 v6, v5, v7
	v_fmamk_f32 v8, v6, 0x3e76c4e1, v195
	v_fmaak_f32 v8, v6, v8, 0x3ecccdef
	v_sub_f32_e32 v5, v6, v5
	v_sub_f32_e32 v15, v7, v5
	v_mul_f32_e32 v5, v6, v8
	v_fma_f32 v7, v6, v8, -v5
	v_fmac_f32_e32 v7, v15, v8
	v_add_f32_e32 v8, v5, v7
	v_add_f32_e32 v9, 0x3f2aaaaa, v8
	v_sub_f32_e32 v5, v8, v5
	v_sub_f32_e32 v5, v7, v5
	v_add_f32_e32 v7, 0xbf2aaaaa, v9
	v_add_f32_e32 v5, 0x31739010, v5
	v_sub_f32_e32 v7, v8, v7
	v_pk_mul_f32 v[10:11], v[4:5], v[6:7]
	v_pk_add_f32 v[12:13], v[4:5], v[6:7]
	v_fma_f32 v8, v6, v4, -v10
	v_fmac_f32_e32 v8, v6, v14
	v_mov_b32_e32 v11, v13
	v_fmac_f32_e32 v8, v15, v4
	v_pk_add_f32 v[6:7], v[10:11], v[8:9]
	s_movk_i32 s23, 0x204
	v_sub_f32_e32 v5, v6, v10
	v_cvt_f64_f32_e32 v[10:11], v3
	v_frexp_exp_i32_f64_e32 v3, v[10:11]
	v_subbrev_co_u32_e64 v3, s[0:1], 0, v3, s[0:1]
	v_cvt_f32_i32_e32 v3, v3
	v_sub_f32_e32 v5, v8, v5
	v_sub_f32_e32 v8, v9, v7
	v_add_f32_e32 v12, v13, v8
	v_pk_mul_f32 v[8:9], v[6:7], v[6:7] op_sel:[0,1] op_sel_hi:[1,0]
	s_mov_b32 s0, 0x3f317218
	v_fma_f32 v10, v6, v7, -v8
	v_fmac_f32_e32 v10, v6, v12
	v_mul_f32_e32 v6, 0x3f317218, v3
	v_fmac_f32_e32 v10, v5, v7
	v_fma_f32 v12, v3, s0, -v6
	v_fmac_f32_e32 v12, 0xb102e308, v3
	v_ldexp_f32 v13, v4, 1
	v_add_f32_e32 v7, v8, v10
	v_pk_add_f32 v[4:5], v[6:7], v[12:13]
	v_ldexp_f32 v3, v14, 1
	v_mov_b32_e32 v14, v7
	v_mov_b32_e32 v15, v5
	v_mov_b32_e32 v9, v13
	v_pk_add_f32 v[8:9], v[14:15], v[8:9] neg_lo:[0,1] neg_hi:[0,1]
	v_mov_b32_e32 v11, v7
	v_pk_add_f32 v[8:9], v[10:11], v[8:9] neg_lo:[0,1] neg_hi:[0,1]
	v_readlane_b32 s0, v244, 43
	v_add_f32_e32 v3, v3, v8
	v_add_f32_e32 v7, v3, v9
	v_pk_add_f32 v[8:9], v[4:5], v[6:7] neg_lo:[0,1] neg_hi:[0,1]
	v_pk_add_f32 v[10:11], v[4:5], v[6:7]
	v_mov_b32_e32 v13, v4
	v_mov_b32_e32 v9, v11
	v_readlane_b32 s1, v244, 44
	s_mov_b32 s24, s0
	s_lshl_b32 s0, s0, 7
	v_pk_add_f32 v[14:15], v[12:13], v[8:9] neg_lo:[0,1] neg_hi:[0,1]
	v_pk_add_f32 v[8:9], v[12:13], v[8:9]
	s_ashr_i32 s1, s0, 31
	v_pk_add_f32 v[12:13], v[8:9], v[4:5] op_sel:[1,0] op_sel_hi:[0,1] neg_lo:[0,1] neg_hi:[0,1]
	s_lshl_b64 s[0:1], s[0:1], 2
	v_pk_add_f32 v[16:17], v[10:11], v[12:13] op_sel_hi:[1,0] neg_lo:[0,1] neg_hi:[0,1]
	v_mov_b32_e32 v10, v11
	v_mov_b32_e32 v11, v9
	v_pk_mov_b32 v[12:13], v[4:5], v[12:13] op_sel:[1,0]
	s_add_u32 s20, s46, s0
	v_pk_add_f32 v[10:11], v[10:11], v[12:13] neg_lo:[0,1] neg_hi:[0,1]
	v_mov_b32_e32 v6, v7
	v_mov_b32_e32 v7, v4
	s_addc_u32 s21, s47, s1
	v_pk_add_f32 v[4:5], v[6:7], v[10:11] neg_lo:[0,1] neg_hi:[0,1]
	global_load_dword v3, v168, s[20:21] offset:256
	global_load_dword v7, v168, s[20:21] offset:384
	v_mov_b32_e32 v16, v14
	v_pk_add_f32 v[10:11], v[16:17], v[4:5]
	v_mov_b32_e32 v15, v9
	v_pk_add_f32 v[12:13], v[10:11], v[10:11] op_sel:[0,1] op_sel_hi:[1,0]
	s_mov_b32 s22, 0x42b17218
	v_pk_add_f32 v[8:9], v[8:9], v[12:13] op_sel:[1,0] op_sel_hi:[0,1]
	v_mov_b32_e32 v11, v8
	v_pk_add_f32 v[16:17], v[10:11], v[14:15] neg_lo:[0,1] neg_hi:[0,1]
	v_mov_b32_e32 v5, v12
	v_sub_f32_e32 v6, v10, v16
	v_pk_add_f32 v[4:5], v[4:5], v[16:17] neg_lo:[0,1] neg_hi:[0,1]
	v_sub_f32_e32 v6, v14, v6
	v_add_f32_e32 v4, v4, v6
	v_add_f32_e32 v4, v4, v5
	v_add_f32_e32 v5, v8, v4
	v_sub_f32_e32 v6, v5, v8
	v_sub_f32_e32 v4, v4, v6
	v_mul_f32_e32 v6, v18, v5
	v_fma_f32 v5, v18, v5, -v6
	v_fmac_f32_e32 v5, v18, v4
	v_add_f32_e32 v4, v6, v5
	v_cmp_class_f32_e64 s[0:1], v6, s23
	v_sub_f32_e32 v8, v4, v6
	v_sub_f32_e32 v5, v5, v8
	v_cndmask_b32_e64 v4, v4, v6, s[0:1]
	v_cmp_eq_f32_e64 s[0:1], s22, v4
	v_readlane_b32 s44, v247, 20
	v_readlane_b32 s45, v247, 21
	v_cndmask_b32_e64 v6, 0, v212, s[0:1]
	v_sub_f32_e32 v8, v4, v6
	v_mul_f32_e32 v9, 0x3fb8aa3b, v8
	s_mov_b32 s0, 0x3fb8aa3b
	v_fma_f32 v10, v8, s0, -v9
	v_rndne_f32_e32 v11, v9
	v_fmac_f32_e32 v10, 0x32a5705f, v8
	v_sub_f32_e32 v9, v9, v11
	v_add_f32_e32 v9, v9, v10
	v_exp_f32_e32 v9, v9
	v_cvt_i32_f32_e32 v10, v11
	s_mov_b32 s0, 0x7f800000
; __device__ __forceinline__ float bf2f(u16 h) { return __uint_as_float(((unsigned)h) << 16); }
; __device__ __forceinline__ float lo2f(unsigned u) { return __uint_as_float(u << 16); }
; __device__ __forceinline__ float hi2f(unsigned u) { return __uint_as_float(u & 0xffff0000u); }
; __device__ __forceinline__ void phase_mla_post(const Params p, int l, char* smem) {
;     ...
;   for (int s = lbid() * 4 + w; s < S_; s += gridDim.x * 4) {
;     float ang = (float)pos[s] * inv_freq;
;     const float nrev = rintf(ang * 0.15915494309189535f);
;     float rr_ = fmaf(-nrev, 6.28125f, ang);
;     rr_ = fmaf(-nrev, 1.9353071795864769e-3f, rr_);
;     const float rev = rr_ * 0.15915494309189535f;
;     float cs = __builtin_amdgcn_cosf(rev), sn = __builtin_amdgcn_sinf(rev);
;     const u16* mq = (const u16*)(ws + OFF_MQ) + (size_t)s * 768;
;     const u16* mk = (const u16*)(ws + OFF_MKV) + (size_t)s * 512;
;     float kr1, kr2;
;     {
;       const u16* kr = (const u16*)(ws + OFF_P) + (size_t)s * NINP + O_KR;
;       float t1 = lane < 32 ? bf2f(kr[fi]) : 0.f, t2 = lane < 32 ? bf2f(kr[32 + fi]) : 0.f;
;       float ss = wave_sum(t1 * t1 + t2 * t2);
;       float rs = rsqrtf(ss * (1.f / 64) + 1e-6f);
;       t1 *= rs * rg[64 + fi];
;       t2 *= rs * rg[64 + 32 + fi];
;       kr1 = t1 * cs - t2 * sn;
;       kr2 = t2 * cs + t1 * sn;
;     }
; #pragma unroll
;     for (int h = 0; h < 4; ++h) {
;       u16* qd = (u16*)(ws + OFF_QM) + ((size_t)h * S_ + s) * 192;
;       u16* kd = (u16*)(ws + OFF_KM) + ((size_t)h * S_ + s) * 192;
;       {
;         const unsigned ab = *(const unsigned*)(mq + h * 192 + 2 * lane);
;         float a = lo2f(ab), b = hi2f(ab);
;         float ss = wave_sum(a * a + b * b);
;         float rs = rsqrtf(ss * (1.f / 128) + 1e-6f) * qscale;
;         const float2 gq = *(const float2*)(ng + 2 * lane);
;         *(unsigned*)(qd + 2 * lane) = pack2(a * rs * gq.x, b * rs * gq.y);
;       }
;       {
;         float t1 = lane < 32 ? bf2f(mq[h * 192 + 128 + fi]) : 0.f, t2 = lane < 32 ? bf2f(mq[h * 192 + 160 + fi]) : 0.f;
	v_cmp_neq_f32_e64 s[0:1], |v4|, s0
	v_and_b32_e32 v1, 63, v1
	v_readlane_b32 s48, v247, 24
	v_cndmask_b32_e64 v4, 0, v5, s[0:1]
	s_mov_b32 s0, 0xc2ce8ed0
	v_ldexp_f32 v5, v9, v10
	v_cmp_ngt_f32_e64 s[0:1], s0, v8
	v_add_f32_e32 v4, v6, v4
	v_readlane_b32 s50, v247, 26
	v_cndmask_b32_e64 v5, 0, v5, s[0:1]
	v_cmp_nlt_f32_e64 s[0:1], s22, v8
	v_readlane_b32 s51, v247, 27
	v_readlane_b32 s48, v244, 34
	v_cndmask_b32_e64 v5, v208, v5, s[0:1]
	v_fma_f32 v4, v5, v4, v5
	v_cmp_class_f32_e64 s[0:1], v5, s23
	s_movk_i32 s51, 0x3ff
	v_readlane_b32 s50, v244, 33
	v_cndmask_b32_e64 v4, v4, v5, s[0:1]
	v_cmp_neq_f32_e64 s[0:1], v18, |v18|
	v_lshlrev_b32_e32 v6, 1, v1
	v_readlane_b32 s37, v247, 13
	v_cndmask_b32_e64 v5, v208, 0, s[0:1]
	v_cndmask_b32_e64 v5, v5, 1.0, vcc
	v_cmp_class_f32_e64 s[0:1], v18, s23
	v_cmp_gt_u32_e32 vcc, 32, v1
	v_readlane_b32 s38, v247, 14
	v_cndmask_b32_e64 v28, |v4|, v5, s[0:1]
	s_lshl_b32 s0, s24, 8
	s_ashr_i32 s1, s0, 31
	s_lshl_b64 s[0:1], s[0:1], 2
	s_add_u32 s22, s44, s0
	s_addc_u32 s23, s45, s1
	v_cmp_lt_i32_e64 s[0:1], v199, v198
	v_readlane_b32 s39, v247, 15
	v_readlane_b32 s40, v247, 16
	v_cndmask_b32_e64 v4, v197, v199, s[0:1]
	v_cmp_lt_i32_e64 s[0:1], v200, v198
	v_lshlrev_b32_e32 v29, 2, v4
	v_readlane_b32 s41, v247, 17
	v_cndmask_b32_e64 v4, v197, v200, s[0:1]
	v_cmp_lt_i32_e64 s[0:1], v201, v198
	v_lshlrev_b32_e32 v30, 2, v4
	v_readlane_b32 s42, v247, 18
	v_cndmask_b32_e64 v4, v197, v201, s[0:1]
	v_cmp_lt_i32_e64 s[0:1], v202, v198
	v_lshlrev_b32_e32 v31, 2, v4
	v_readlane_b32 s43, v247, 19
	v_cndmask_b32_e64 v4, v197, v202, s[0:1]
	v_cmp_lt_i32_e64 s[0:1], v203, v198
	v_lshlrev_b32_e32 v32, 2, v4
	v_readlane_b32 s49, v247, 25
	v_cndmask_b32_e64 v4, v197, v203, s[0:1]
	v_cmp_lt_i32_e64 s[0:1], v204, v198
	v_lshlrev_b32_e32 v33, 2, v4
	s_nop 0
	v_cndmask_b32_e64 v4, v197, v204, s[0:1]
	v_lshlrev_b32_e32 v34, 2, v4
	v_lshl_add_u64 v[4:5], s[20:21], 0, v[168:169]
	v_lshlrev_b32_e32 v168, 3, v1
	v_readlane_b32 s0, v246, 4
	v_lshl_add_u64 v[8:9], s[22:23], 0, v[168:169]
	v_lshlrev_b32_e32 v168, 2, v1
	v_readlane_b32 s1, v246, 5
	s_mov_b64 s[20:21], 0
	s_nop 0
	v_lshl_add_u64 v[10:11], s[0:1], 0, v[168:169]
	s_cmpk_lg_u32 s72, 0x800
	s_cbranch_scc1 .LBB0_255
	v_mov_b32_e32 v42, v0
	v_and_b32_e32 v43, 63, v171
	v_lshlrev_b32_e32 v43, 2, v43
	v_lshlrev_b32_e32 v44, 1, v2
	v_and_b32_e32 v45, 63, v171
	v_cmp_gt_u32_e64 s[22:23], 32, v45
	global_load_dwordx2 v[46:47], v[8:9], off
	global_load_dwordx2 v[48:49], v[8:9], off offset:512
	global_load_dword v45, v[4:5], off
	global_load_dword v50, v[4:5], off offset:128
	global_load_dword v51, v[4:5], off offset:256
	global_load_dword v52, v[4:5], off offset:384
.Lmp_tok:
	v_readfirstlane_b32 s20, v42
	s_nop 3
	s_mul_i32 s21, s20, 0x600
	s_add_u32 s21, s21, 0x33480000
	v_add_u32_e32 v72, s21, v43
	s_lshl_b32 s21, s20, 10
	s_add_u32 s21, s21, 0x34c80000
	v_add_u32_e32 v73, s21, v43
	s_mul_i32 s21, s20, 0x7400
	s_add_u32 s21, s21, 0x16441f00
	v_add_u32_e32 v74, s21, v44
	s_mul_i32 s21, s20, 0x600
	s_add_u32 s21, s21, 0x33480000
	v_add_u32_e32 v78, s21, v44
	v_readlane_b32 s24, v245, 60
	v_readlane_b32 s25, v245, 61
	s_lshl_b32 s21, s20, 2
	v_mov_b32_e32 v75, s21
	s_nop 2
	global_load_dword v53, v75, s[24:25]
	global_load_ushort v54, v74, s[96:97]
	global_load_ushort v55, v74, s[96:97] offset:64
	global_load_dword v56, v72, s[96:97]
	global_load_ushort v60, v78, s[96:97] offset:256
	global_load_ushort v61, v78, s[96:97] offset:320
	global_load_dword v68, v73, s[96:97]
	global_load_dword v57, v72, s[96:97] offset:384
	global_load_ushort v62, v78, s[96:97] offset:640
	global_load_ushort v63, v78, s[96:97] offset:704
	global_load_dword v69, v73, s[96:97] offset:256
	global_load_dword v58, v72, s[96:97] offset:768
	global_load_ushort v64, v78, s[96:97] offset:1024
	global_load_ushort v65, v78, s[96:97] offset:1088
	global_load_dword v70, v73, s[96:97] offset:512
	global_load_dword v59, v72, s[96:97] offset:1152
	global_load_ushort v66, v78, s[96:97] offset:1408
	global_load_ushort v67, v78, s[96:97] offset:1472
	global_load_dword v71, v73, s[96:97] offset:768
	s_waitcnt vmcnt(0)
	v_cvt_f32_i32_e32 v107, v53
	v_mul_f32_e32 v107, v28, v107
	v_mul_f32_e32 v108, 0.15915494, v107
	v_rndne_f32_e32 v108, v108
	v_fmac_f32_e32 v107, 0xc0c90000, v108
	v_fmac_f32_e32 v107, 0xbafdaa22, v108
	v_mul_f32_e32 v107, 0.15915494, v107
	v_cos_f32_e32 v105, v107
	v_sin_f32_e32 v106, v107
	v_lshlrev_b32_e32 v54, 16, v54
	v_cndmask_b32_e64 v54, 0, v54, s[22:23]
	v_lshlrev_b32_e32 v55, 16, v55
	v_cndmask_b32_e64 v55, 0, v55, s[22:23]
	v_lshlrev_b32_e32 v60, 16, v60
	v_cndmask_b32_e64 v60, 0, v60, s[22:23]
	v_lshlrev_b32_e32 v61, 16, v61
	v_cndmask_b32_e64 v61, 0, v61, s[22:23]
	v_lshlrev_b32_e32 v62, 16, v62
	v_cndmask_b32_e64 v62, 0, v62, s[22:23]
	v_lshlrev_b32_e32 v63, 16, v63
	v_cndmask_b32_e64 v63, 0, v63, s[22:23]
	v_lshlrev_b32_e32 v64, 16, v64
	v_cndmask_b32_e64 v64, 0, v64, s[22:23]
	v_lshlrev_b32_e32 v65, 16, v65
	v_cndmask_b32_e64 v65, 0, v65, s[22:23]
	v_lshlrev_b32_e32 v66, 16, v66
	v_cndmask_b32_e64 v66, 0, v66, s[22:23]
	v_lshlrev_b32_e32 v67, 16, v67
	v_cndmask_b32_e64 v67, 0, v67, s[22:23]
	v_lshlrev_b32_e32 v110, 16, v56
	v_and_b32_e32 v111, 0xffff0000, v56
	v_lshlrev_b32_e32 v118, 16, v68
	v_and_b32_e32 v119, 0xffff0000, v68
	v_lshlrev_b32_e32 v112, 16, v57
	v_and_b32_e32 v113, 0xffff0000, v57
	v_lshlrev_b32_e32 v120, 16, v69
	v_and_b32_e32 v121, 0xffff0000, v69
	v_lshlrev_b32_e32 v114, 16, v58
	v_and_b32_e32 v115, 0xffff0000, v58
	v_lshlrev_b32_e32 v122, 16, v70
	v_and_b32_e32 v123, 0xffff0000, v70
	v_lshlrev_b32_e32 v116, 16, v59
	v_and_b32_e32 v117, 0xffff0000, v59
; __device__ __forceinline__ u16 f2bf(float f) { return (u16)(pack2(f, 0.f) & 0xffffu); }
; __device__ __forceinline__ float bf2f(u16 h) { return __uint_as_float(((unsigned)h) << 16); }
; __device__ __forceinline__ float lo2f(unsigned u) { return __uint_as_float(u << 16); }
; __device__ __forceinline__ float hi2f(unsigned u) { return __uint_as_float(u & 0xffff0000u); }
; __device__ __forceinline__ void phase_mla_post(const Params p, int l, char* smem) {
;     ...
;       float t1 = lane < 32 ? bf2f(kr[fi]) : 0.f, t2 = lane < 32 ? bf2f(kr[32 + fi]) : 0.f;
;       float ss = wave_sum(t1 * t1 + t2 * t2);
;       float rs = rsqrtf(ss * (1.f / 64) + 1e-6f);
;       t1 *= rs * rg[64 + fi];
;       t2 *= rs * rg[64 + 32 + fi];
;       kr1 = t1 * cs - t2 * sn;
;       kr2 = t2 * cs + t1 * sn;
;     }
; #pragma unroll
;     for (int h = 0; h < 4; ++h) {
;       u16* qd = (u16*)(ws + OFF_QM) + ((size_t)h * S_ + s) * 192;
;       u16* kd = (u16*)(ws + OFF_KM) + ((size_t)h * S_ + s) * 192;
;       {
;         const unsigned ab = *(const unsigned*)(mq + h * 192 + 2 * lane);
;         float a = lo2f(ab), b = hi2f(ab);
;         float ss = wave_sum(a * a + b * b);
;         float rs = rsqrtf(ss * (1.f / 128) + 1e-6f) * qscale;
;         const float2 gq = *(const float2*)(ng + 2 * lane);
;         *(unsigned*)(qd + 2 * lane) = pack2(a * rs * gq.x, b * rs * gq.y);
;       }
;       {
;         float t1 = lane < 32 ? bf2f(mq[h * 192 + 128 + fi]) : 0.f, t2 = lane < 32 ? bf2f(mq[h * 192 + 160 + fi]) : 0.f;
;         float ss = wave_sum(t1 * t1 + t2 * t2);
;         float rs = rsqrtf(ss * (1.f / 64) + 1e-6f);
;         t1 *= rs * rg[fi];
;         t2 *= rs * rg[32 + fi];
;         if (lane < 32) {
;           qd[128 + fi] = f2bf((t1 * cs - t2 * sn) * qscale);
;           qd[160 + fi] = f2bf((t2 * cs + t1 * sn) * qscale);
;         }
;       }
;       {
;         const unsigned ab = *(const unsigned*)(mk + h * 128 + 2 * lane);
;         float a = lo2f(ab), b = hi2f(ab);
;         float ss = wave_sum(a * a + b * b);
	v_lshlrev_b32_e32 v124, 16, v71
	v_and_b32_e32 v125, 0xffff0000, v71
	v_mul_f32_e32 v79, v54, v54
	v_fmac_f32_e32 v79, v55, v55
	v_mul_f32_e32 v80, v110, v110
	v_fmac_f32_e32 v80, v111, v111
	v_mul_f32_e32 v81, v60, v60
	v_fmac_f32_e32 v81, v61, v61
	v_mul_f32_e32 v82, v118, v118
	v_fmac_f32_e32 v82, v119, v119
	v_mul_f32_e32 v83, v112, v112
	v_fmac_f32_e32 v83, v113, v113
	v_mul_f32_e32 v84, v62, v62
	v_fmac_f32_e32 v84, v63, v63
	v_mul_f32_e32 v85, v120, v120
	v_fmac_f32_e32 v85, v121, v121
	v_mul_f32_e32 v86, v114, v114
	v_fmac_f32_e32 v86, v115, v115
	v_mul_f32_e32 v87, v64, v64
	v_fmac_f32_e32 v87, v65, v65
	v_mul_f32_e32 v88, v122, v122
	v_fmac_f32_e32 v88, v123, v123
	v_mul_f32_e32 v89, v116, v116
	v_fmac_f32_e32 v89, v117, v117
	v_mul_f32_e32 v90, v66, v66
	v_fmac_f32_e32 v90, v67, v67
	v_mul_f32_e32 v91, v124, v124
	v_fmac_f32_e32 v91, v125, v125
	v_add_f32_dpp v79, v79, v79 quad_perm:[1,0,3,2] row_mask:0xf bank_mask:0xf bound_ctrl:1
	v_add_f32_dpp v80, v80, v80 quad_perm:[1,0,3,2] row_mask:0xf bank_mask:0xf bound_ctrl:1
	v_add_f32_dpp v81, v81, v81 quad_perm:[1,0,3,2] row_mask:0xf bank_mask:0xf bound_ctrl:1
	v_add_f32_dpp v82, v82, v82 quad_perm:[1,0,3,2] row_mask:0xf bank_mask:0xf bound_ctrl:1
	v_add_f32_dpp v83, v83, v83 quad_perm:[1,0,3,2] row_mask:0xf bank_mask:0xf bound_ctrl:1
	v_add_f32_dpp v84, v84, v84 quad_perm:[1,0,3,2] row_mask:0xf bank_mask:0xf bound_ctrl:1
	v_add_f32_dpp v85, v85, v85 quad_perm:[1,0,3,2] row_mask:0xf bank_mask:0xf bound_ctrl:1
	v_add_f32_dpp v86, v86, v86 quad_perm:[1,0,3,2] row_mask:0xf bank_mask:0xf bound_ctrl:1
	v_add_f32_dpp v87, v87, v87 quad_perm:[1,0,3,2] row_mask:0xf bank_mask:0xf bound_ctrl:1
	v_add_f32_dpp v88, v88, v88 quad_perm:[1,0,3,2] row_mask:0xf bank_mask:0xf bound_ctrl:1
	v_add_f32_dpp v89, v89, v89 quad_perm:[1,0,3,2] row_mask:0xf bank_mask:0xf bound_ctrl:1
	v_add_f32_dpp v90, v90, v90 quad_perm:[1,0,3,2] row_mask:0xf bank_mask:0xf bound_ctrl:1
	v_add_f32_dpp v91, v91, v91 quad_perm:[1,0,3,2] row_mask:0xf bank_mask:0xf bound_ctrl:1
	v_add_f32_dpp v79, v79, v79 quad_perm:[2,3,0,1] row_mask:0xf bank_mask:0xf bound_ctrl:1
	v_add_f32_dpp v80, v80, v80 quad_perm:[2,3,0,1] row_mask:0xf bank_mask:0xf bound_ctrl:1
	v_add_f32_dpp v81, v81, v81 quad_perm:[2,3,0,1] row_mask:0xf bank_mask:0xf bound_ctrl:1
	v_add_f32_dpp v82, v82, v82 quad_perm:[2,3,0,1] row_mask:0xf bank_mask:0xf bound_ctrl:1
	v_add_f32_dpp v83, v83, v83 quad_perm:[2,3,0,1] row_mask:0xf bank_mask:0xf bound_ctrl:1
	v_add_f32_dpp v84, v84, v84 quad_perm:[2,3,0,1] row_mask:0xf bank_mask:0xf bound_ctrl:1
	v_add_f32_dpp v85, v85, v85 quad_perm:[2,3,0,1] row_mask:0xf bank_mask:0xf bound_ctrl:1
	v_add_f32_dpp v86, v86, v86 quad_perm:[2,3,0,1] row_mask:0xf bank_mask:0xf bound_ctrl:1
	v_add_f32_dpp v87, v87, v87 quad_perm:[2,3,0,1] row_mask:0xf bank_mask:0xf bound_ctrl:1
	v_add_f32_dpp v88, v88, v88 quad_perm:[2,3,0,1] row_mask:0xf bank_mask:0xf bound_ctrl:1
	v_add_f32_dpp v89, v89, v89 quad_perm:[2,3,0,1] row_mask:0xf bank_mask:0xf bound_ctrl:1
	v_add_f32_dpp v90, v90, v90 quad_perm:[2,3,0,1] row_mask:0xf bank_mask:0xf bound_ctrl:1
	v_add_f32_dpp v91, v91, v91 quad_perm:[2,3,0,1] row_mask:0xf bank_mask:0xf bound_ctrl:1
	v_add_f32_dpp v79, v79, v79 row_half_mirror row_mask:0xf bank_mask:0xf bound_ctrl:1
	v_add_f32_dpp v80, v80, v80 row_half_mirror row_mask:0xf bank_mask:0xf bound_ctrl:1
	v_add_f32_dpp v81, v81, v81 row_half_mirror row_mask:0xf bank_mask:0xf bound_ctrl:1
	v_add_f32_dpp v82, v82, v82 row_half_mirror row_mask:0xf bank_mask:0xf bound_ctrl:1
	v_add_f32_dpp v83, v83, v83 row_half_mirror row_mask:0xf bank_mask:0xf bound_ctrl:1
	v_add_f32_dpp v84, v84, v84 row_half_mirror row_mask:0xf bank_mask:0xf bound_ctrl:1
	v_add_f32_dpp v85, v85, v85 row_half_mirror row_mask:0xf bank_mask:0xf bound_ctrl:1
	v_add_f32_dpp v86, v86, v86 row_half_mirror row_mask:0xf bank_mask:0xf bound_ctrl:1
	v_add_f32_dpp v87, v87, v87 row_half_mirror row_mask:0xf bank_mask:0xf bound_ctrl:1
	v_add_f32_dpp v88, v88, v88 row_half_mirror row_mask:0xf bank_mask:0xf bound_ctrl:1
	v_add_f32_dpp v89, v89, v89 row_half_mirror row_mask:0xf bank_mask:0xf bound_ctrl:1
	v_add_f32_dpp v90, v90, v90 row_half_mirror row_mask:0xf bank_mask:0xf bound_ctrl:1
	v_add_f32_dpp v91, v91, v91 row_half_mirror row_mask:0xf bank_mask:0xf bound_ctrl:1
	v_add_f32_dpp v79, v79, v79 row_mirror row_mask:0xf bank_mask:0xf bound_ctrl:1
	v_add_f32_dpp v80, v80, v80 row_mirror row_mask:0xf bank_mask:0xf bound_ctrl:1
	v_add_f32_dpp v81, v81, v81 row_mirror row_mask:0xf bank_mask:0xf bound_ctrl:1
	v_add_f32_dpp v82, v82, v82 row_mirror row_mask:0xf bank_mask:0xf bound_ctrl:1
	v_add_f32_dpp v83, v83, v83 row_mirror row_mask:0xf bank_mask:0xf bound_ctrl:1
	v_add_f32_dpp v84, v84, v84 row_mirror row_mask:0xf bank_mask:0xf bound_ctrl:1
	v_add_f32_dpp v85, v85, v85 row_mirror row_mask:0xf bank_mask:0xf bound_ctrl:1
	v_add_f32_dpp v86, v86, v86 row_mirror row_mask:0xf bank_mask:0xf bound_ctrl:1
	v_add_f32_dpp v87, v87, v87 row_mirror row_mask:0xf bank_mask:0xf bound_ctrl:1
	v_add_f32_dpp v88, v88, v88 row_mirror row_mask:0xf bank_mask:0xf bound_ctrl:1
	v_add_f32_dpp v89, v89, v89 row_mirror row_mask:0xf bank_mask:0xf bound_ctrl:1
	v_add_f32_dpp v90, v90, v90 row_mirror row_mask:0xf bank_mask:0xf bound_ctrl:1
	v_add_f32_dpp v91, v91, v91 row_mirror row_mask:0xf bank_mask:0xf bound_ctrl:1
	ds_bpermute_b32 v92, v30, v79
	ds_bpermute_b32 v93, v30, v80
	ds_bpermute_b32 v94, v30, v81
	ds_bpermute_b32 v95, v30, v82
	ds_bpermute_b32 v96, v30, v83
	ds_bpermute_b32 v97, v30, v84
	ds_bpermute_b32 v98, v30, v85
	ds_bpermute_b32 v99, v30, v86
	ds_bpermute_b32 v100, v30, v87
	ds_bpermute_b32 v101, v30, v88
	ds_bpermute_b32 v102, v30, v89
	ds_bpermute_b32 v103, v30, v90
	ds_bpermute_b32 v104, v30, v91
	s_waitcnt lgkmcnt(0)
; __device__ __forceinline__ u16 f2bf(float f) { return (u16)(pack2(f, 0.f) & 0xffffu); }
; __device__ __forceinline__ float bf2f(u16 h) { return __uint_as_float(((unsigned)h) << 16); }
; __device__ __forceinline__ float lo2f(unsigned u) { return __uint_as_float(u << 16); }
; __device__ __forceinline__ float hi2f(unsigned u) { return __uint_as_float(u & 0xffff0000u); }
; __device__ __forceinline__ void phase_mla_post(const Params p, int l, char* smem) {
;     ...
;         const unsigned ab = *(const unsigned*)(mq + h * 192 + 2 * lane);
;         float a = lo2f(ab), b = hi2f(ab);
;         float ss = wave_sum(a * a + b * b);
;         float rs = rsqrtf(ss * (1.f / 128) + 1e-6f) * qscale;
;         const float2 gq = *(const float2*)(ng + 2 * lane);
;         *(unsigned*)(qd + 2 * lane) = pack2(a * rs * gq.x, b * rs * gq.y);
;       }
;       {
;         float t1 = lane < 32 ? bf2f(mq[h * 192 + 128 + fi]) : 0.f, t2 = lane < 32 ? bf2f(mq[h * 192 + 160 + fi]) : 0.f;
;         float ss = wave_sum(t1 * t1 + t2 * t2);
;         float rs = rsqrtf(ss * (1.f / 64) + 1e-6f);
;         t1 *= rs * rg[fi];
;         t2 *= rs * rg[32 + fi];
;         if (lane < 32) {
;           qd[128 + fi] = f2bf((t1 * cs - t2 * sn) * qscale);
;           qd[160 + fi] = f2bf((t2 * cs + t1 * sn) * qscale);
;         }
;       }
;       {
;         const unsigned ab = *(const unsigned*)(mk + h * 128 + 2 * lane);
;         float a = lo2f(ab), b = hi2f(ab);
;         float ss = wave_sum(a * a + b * b);
	v_add_f32_e32 v79, v79, v92
	v_add_f32_e32 v80, v80, v93
	v_add_f32_e32 v81, v81, v94
	v_add_f32_e32 v82, v82, v95
	v_add_f32_e32 v83, v83, v96
	v_add_f32_e32 v84, v84, v97
	v_add_f32_e32 v85, v85, v98
	v_add_f32_e32 v86, v86, v99
	v_add_f32_e32 v87, v87, v100
	v_add_f32_e32 v88, v88, v101
	v_add_f32_e32 v89, v89, v102
	v_add_f32_e32 v90, v90, v103
	v_add_f32_e32 v91, v91, v104
	ds_bpermute_b32 v92, v29, v79
	ds_bpermute_b32 v93, v29, v80
	ds_bpermute_b32 v94, v29, v81
	ds_bpermute_b32 v95, v29, v82
	ds_bpermute_b32 v96, v29, v83
	ds_bpermute_b32 v97, v29, v84
	ds_bpermute_b32 v98, v29, v85
	ds_bpermute_b32 v99, v29, v86
	ds_bpermute_b32 v100, v29, v87
	ds_bpermute_b32 v101, v29, v88
	ds_bpermute_b32 v102, v29, v89
	ds_bpermute_b32 v103, v29, v90
	ds_bpermute_b32 v104, v29, v91
	s_waitcnt lgkmcnt(0)
; __device__ __forceinline__ u16 f2bf(float f) { return (u16)(pack2(f, 0.f) & 0xffffu); }
; __device__ __forceinline__ float bf2f(u16 h) { return __uint_as_float(((unsigned)h) << 16); }
; __device__ __forceinline__ float lo2f(unsigned u) { return __uint_as_float(u << 16); }
; __device__ __forceinline__ float hi2f(unsigned u) { return __uint_as_float(u & 0xffff0000u); }
; __device__ __forceinline__ void phase_mla_post(const Params p, int l, char* smem) {
;     ...
;       float ss = wave_sum(t1 * t1 + t2 * t2);
;       float rs = rsqrtf(ss * (1.f / 64) + 1e-6f);
;       t1 *= rs * rg[64 + fi];
;       t2 *= rs * rg[64 + 32 + fi];
;       kr1 = t1 * cs - t2 * sn;
;       kr2 = t2 * cs + t1 * sn;
;     }
; #pragma unroll
;     for (int h = 0; h < 4; ++h) {
;       u16* qd = (u16*)(ws + OFF_QM) + ((size_t)h * S_ + s) * 192;
;       u16* kd = (u16*)(ws + OFF_KM) + ((size_t)h * S_ + s) * 192;
;       {
;         const unsigned ab = *(const unsigned*)(mq + h * 192 + 2 * lane);
;         float a = lo2f(ab), b = hi2f(ab);
;         float ss = wave_sum(a * a + b * b);
;         float rs = rsqrtf(ss * (1.f / 128) + 1e-6f) * qscale;
;         const float2 gq = *(const float2*)(ng + 2 * lane);
;         *(unsigned*)(qd + 2 * lane) = pack2(a * rs * gq.x, b * rs * gq.y);
;       }
;       {
;         float t1 = lane < 32 ? bf2f(mq[h * 192 + 128 + fi]) : 0.f, t2 = lane < 32 ? bf2f(mq[h * 192 + 160 + fi]) : 0.f;
;         float ss = wave_sum(t1 * t1 + t2 * t2);
;         float rs = rsqrtf(ss * (1.f / 64) + 1e-6f);
;         t1 *= rs * rg[fi];
;         t2 *= rs * rg[32 + fi];
;         if (lane < 32) {
;           qd[128 + fi] = f2bf((t1 * cs - t2 * sn) * qscale);
;           qd[160 + fi] = f2bf((t2 * cs + t1 * sn) * qscale);
;         }
;       }
;       {
;         const unsigned ab = *(const unsigned*)(mk + h * 128 + 2 * lane);
;         float a = lo2f(ab), b = hi2f(ab);
;         float ss = wave_sum(a * a + b * b);
;         float rs = rsqrtf(ss * (1.f / 128) + 1e-6f);
;         const float2 gk = *(const float2*)(ng + 128 + 2 * lane);
;         *(unsigned*)(kd + 2 * lane) = pack2(a * rs * gk.x, b * rs * gk.y);
;         if (lane < 32) {
;           kd[128 + fi] = f2bf(kr1);
;           kd[160 + fi] = f2bf(kr2);
;         }
;       }
	v_add_f32_e32 v79, v79, v92
	v_add_f32_e32 v80, v80, v93
	v_add_f32_e32 v81, v81, v94
	v_add_f32_e32 v82, v82, v95
	v_add_f32_e32 v83, v83, v96
	v_add_f32_e32 v84, v84, v97
	v_add_f32_e32 v85, v85, v98
	v_add_f32_e32 v86, v86, v99
	v_add_f32_e32 v87, v87, v100
	v_add_f32_e32 v88, v88, v101
	v_add_f32_e32 v89, v89, v102
	v_add_f32_e32 v90, v90, v103
	v_add_f32_e32 v91, v91, v104
	v_fmamk_f32 v79, v79, 0x3c800000, v170
	v_fmamk_f32 v80, v80, 0x3c000000, v170
	v_fmamk_f32 v81, v81, 0x3c800000, v170
	v_fmamk_f32 v82, v82, 0x3c000000, v170
	v_fmamk_f32 v83, v83, 0x3c000000, v170
	v_fmamk_f32 v84, v84, 0x3c800000, v170
	v_fmamk_f32 v85, v85, 0x3c000000, v170
	v_fmamk_f32 v86, v86, 0x3c000000, v170
	v_fmamk_f32 v87, v87, 0x3c800000, v170
	v_fmamk_f32 v88, v88, 0x3c000000, v170
	v_fmamk_f32 v89, v89, 0x3c000000, v170
	v_fmamk_f32 v90, v90, 0x3c800000, v170
	v_fmamk_f32 v91, v91, 0x3c000000, v170
	v_rsq_f32_e32 v79, v79
	v_rsq_f32_e32 v80, v80
	v_rsq_f32_e32 v81, v81
	v_rsq_f32_e32 v82, v82
	v_rsq_f32_e32 v83, v83
	v_rsq_f32_e32 v84, v84
	v_rsq_f32_e32 v85, v85
	v_rsq_f32_e32 v86, v86
	v_rsq_f32_e32 v87, v87
	v_rsq_f32_e32 v88, v88
	v_rsq_f32_e32 v89, v89
	v_rsq_f32_e32 v90, v90
	v_rsq_f32_e32 v91, v91
	s_nop 0
	v_mul_f32_e32 v80, 0x3dd53b94, v80
	v_mul_f32_e32 v83, 0x3dd53b94, v83
	v_mul_f32_e32 v86, 0x3dd53b94, v86
	v_mul_f32_e32 v89, 0x3dd53b94, v89
	v_mul_f32_e32 v92, v79, v51
	v_mul_f32_e32 v93, v79, v52
	v_mul_f32_e32 v54, v54, v92
	v_mul_f32_e32 v55, v55, v93
	v_mul_f32_e32 v109, v55, v106
	v_fma_f32 v109, v54, v105, -v109
	v_mul_f32_e32 v134, v54, v106
	v_fmac_f32_e32 v134, v55, v105
	v_cvt_pk_bf16_f32 v109, v109, v109
	v_cvt_pk_bf16_f32 v134, v134, v134
	s_mul_i32 s21, s20, 0x180
	s_add_u32 s24, s21, 0x35c80000
	s_add_u32 s25, s21, 0x36880000
	v_pk_mul_f32 v[110:111], v[110:111], v[80:81] op_sel_hi:[1,0]
	v_pk_mul_f32 v[110:111], v[110:111], v[46:47]
	v_cvt_pk_bf16_f32 v126, v110, v111
	v_add_u32_e32 v76, s24, v43
	global_store_dword v76, v126, s[96:97]
	v_mul_f32_e32 v118, v118, v82
	v_mul_f32_e32 v119, v119, v82
	v_pk_mul_f32 v[118:119], v[118:119], v[48:49]
	v_cvt_pk_bf16_f32 v128, v118, v119
	v_add_u32_e32 v77, s25, v43
	global_store_dword v77, v128, s[96:97]
	v_mul_f32_e32 v130, v81, v45
	v_mul_f32_e32 v132, v81, v50
	v_mul_f32_e32 v60, v60, v130
	v_mul_f32_e32 v61, v61, v132
	v_mul_f32_e32 v130, v61, v106
	v_fma_f32 v130, v60, v105, -v130
	v_mul_f32_e32 v132, v60, v106
	v_fmac_f32_e32 v132, v61, v105
	v_mul_f32_e32 v130, 0x3dd53b94, v130
	v_mul_f32_e32 v132, 0x3dd53b94, v132
	v_cvt_pk_bf16_f32 v130, v130, v130
	v_cvt_pk_bf16_f32 v132, v132, v132
	v_add_u32_e32 v76, s24, v44
	v_add_u32_e32 v77, s25, v44
	s_mov_b64 s[0:1], exec
	s_and_b64 exec, exec, s[22:23]
	global_store_short v76, v130, s[96:97] offset:256
	global_store_short v76, v132, s[96:97] offset:320
	global_store_short v77, v109, s[96:97] offset:256
	global_store_short v77, v134, s[96:97] offset:320
	s_mov_b64 exec, s[0:1]
	s_add_u32 s24, s21, 0x35f80000
	s_add_u32 s25, s21, 0x36b80000
	v_mul_f32_e32 v112, v112, v83
	v_mul_f32_e32 v113, v113, v83
	v_pk_mul_f32 v[112:113], v[112:113], v[46:47]
	v_cvt_pk_bf16_f32 v126, v112, v113
	v_add_u32_e32 v76, s24, v43
	global_store_dword v76, v126, s[96:97]
	v_mul_f32_e32 v120, v120, v85
	v_mul_f32_e32 v121, v121, v85
	v_pk_mul_f32 v[120:121], v[120:121], v[48:49]
	v_cvt_pk_bf16_f32 v128, v120, v121
	v_add_u32_e32 v77, s25, v43
	global_store_dword v77, v128, s[96:97]
	v_mul_f32_e32 v130, v84, v45
	v_mul_f32_e32 v132, v84, v50
	v_mul_f32_e32 v62, v62, v130
	v_mul_f32_e32 v63, v63, v132
	v_mul_f32_e32 v130, v63, v106
	v_fma_f32 v130, v62, v105, -v130
	v_mul_f32_e32 v132, v62, v106
	v_fmac_f32_e32 v132, v63, v105
	v_mul_f32_e32 v130, 0x3dd53b94, v130
	v_mul_f32_e32 v132, 0x3dd53b94, v132
	v_cvt_pk_bf16_f32 v130, v130, v130
	v_cvt_pk_bf16_f32 v132, v132, v132
	v_add_u32_e32 v76, s24, v44
	v_add_u32_e32 v77, s25, v44
	s_mov_b64 s[0:1], exec
	s_and_b64 exec, exec, s[22:23]
	global_store_short v76, v130, s[96:97] offset:256
	global_store_short v76, v132, s[96:97] offset:320
	global_store_short v77, v109, s[96:97] offset:256
	global_store_short v77, v134, s[96:97] offset:320
	s_mov_b64 exec, s[0:1]
	s_add_u32 s24, s21, 0x36280000
	s_add_u32 s25, s21, 0x36e80000
	v_pk_mul_f32 v[114:115], v[114:115], v[86:87] op_sel_hi:[1,0]
	v_pk_mul_f32 v[114:115], v[114:115], v[46:47]
	v_cvt_pk_bf16_f32 v126, v114, v115
	v_add_u32_e32 v76, s24, v43
	global_store_dword v76, v126, s[96:97]
	v_mul_f32_e32 v122, v122, v88
	v_mul_f32_e32 v123, v123, v88
	v_pk_mul_f32 v[122:123], v[122:123], v[48:49]
	v_cvt_pk_bf16_f32 v128, v122, v123
	v_add_u32_e32 v77, s25, v43
	global_store_dword v77, v128, s[96:97]
	v_mul_f32_e32 v130, v87, v45
	v_mul_f32_e32 v132, v87, v50
	v_mul_f32_e32 v64, v64, v130
	v_mul_f32_e32 v65, v65, v132
	v_mul_f32_e32 v130, v65, v106
	v_fma_f32 v130, v64, v105, -v130
	v_mul_f32_e32 v132, v64, v106
	v_fmac_f32_e32 v132, v65, v105
	v_mul_f32_e32 v130, 0x3dd53b94, v130
	v_mul_f32_e32 v132, 0x3dd53b94, v132
	v_cvt_pk_bf16_f32 v130, v130, v130
	v_cvt_pk_bf16_f32 v132, v132, v132
	v_add_u32_e32 v76, s24, v44
	v_add_u32_e32 v77, s25, v44
	s_mov_b64 s[0:1], exec
	s_and_b64 exec, exec, s[22:23]
	global_store_short v76, v130, s[96:97] offset:256
	global_store_short v76, v132, s[96:97] offset:320
	global_store_short v77, v109, s[96:97] offset:256
	global_store_short v77, v134, s[96:97] offset:320
	s_mov_b64 exec, s[0:1]
	s_add_u32 s24, s21, 0x36580000
	s_add_u32 s25, s21, 0x37180000
	v_mul_f32_e32 v116, v116, v89
	v_mul_f32_e32 v117, v117, v89
	v_pk_mul_f32 v[116:117], v[116:117], v[46:47]
	v_cvt_pk_bf16_f32 v126, v116, v117
	v_add_u32_e32 v76, s24, v43
	global_store_dword v76, v126, s[96:97]
	v_mul_f32_e32 v124, v124, v91
	v_mul_f32_e32 v125, v125, v91
	v_pk_mul_f32 v[124:125], v[124:125], v[48:49]
	v_cvt_pk_bf16_f32 v128, v124, v125
	v_add_u32_e32 v77, s25, v43
	global_store_dword v77, v128, s[96:97]
	v_mul_f32_e32 v130, v90, v45
	v_mul_f32_e32 v132, v90, v50
	v_mul_f32_e32 v66, v66, v130
	v_mul_f32_e32 v67, v67, v132
	v_mul_f32_e32 v130, v67, v106
	v_fma_f32 v130, v66, v105, -v130
	v_mul_f32_e32 v132, v66, v106
	v_fmac_f32_e32 v132, v67, v105
	v_mul_f32_e32 v130, 0x3dd53b94, v130
	v_mul_f32_e32 v132, 0x3dd53b94, v132
	v_cvt_pk_bf16_f32 v130, v130, v130
	v_cvt_pk_bf16_f32 v132, v132, v132
	v_add_u32_e32 v76, s24, v44
	v_add_u32_e32 v77, s25, v44
	s_mov_b64 s[0:1], exec
	s_and_b64 exec, exec, s[22:23]
	global_store_short v76, v130, s[96:97] offset:256
	global_store_short v76, v132, s[96:97] offset:320
	global_store_short v77, v109, s[96:97] offset:256
	global_store_short v77, v134, s[96:97] offset:320
	s_mov_b64 exec, s[0:1]
	v_add_u32_e32 v42, s72, v42
	v_cmp_gt_i32_e32 vcc, 0x2000, v42
	s_cbranch_vccnz .Lmp_tok
	s_branch .LBB0_291
